# LN epilogue row statistics for 7 of 8 row blocks rewritten by hand: packed f32 sums/squares, cross-lane all-reduces interleaved across rows, one masked write block
# baseline (speedup 1.0000x reference)
.LBB0_695:
	s_or_b64 exec, exec, s[12:13]
	v_mov_b32_e32 v242, 0xbc800000
	v_pk_add_f32 v[160:161], v[0:1], v[2:3]
	v_pk_add_f32 v[162:163], v[4:5], v[6:7]
	v_pk_add_f32 v[164:165], v[8:9], v[10:11]
	v_pk_add_f32 v[166:167], v[12:13], v[14:15]
	v_pk_add_f32 v[160:161], v[160:161], v[162:163]
	v_pk_add_f32 v[164:165], v[164:165], v[166:167]
	v_pk_add_f32 v[160:161], v[160:161], v[164:165]
	v_add_f32_e32 v128, v160, v161
	v_pk_add_f32 v[168:169], v[40:41], v[42:43]
	v_pk_add_f32 v[170:171], v[44:45], v[46:47]
	v_pk_add_f32 v[172:173], v[56:57], v[58:59]
	v_pk_add_f32 v[174:175], v[60:61], v[62:63]
	v_pk_add_f32 v[168:169], v[168:169], v[170:171]
	v_pk_add_f32 v[172:173], v[172:173], v[174:175]
	v_pk_add_f32 v[168:169], v[168:169], v[172:173]
	v_add_f32_e32 v130, v168, v169
	v_pk_add_f32 v[160:161], v[24:25], v[26:27]
	v_pk_add_f32 v[162:163], v[28:29], v[30:31]
	v_pk_add_f32 v[164:165], v[32:33], v[34:35]
	v_pk_add_f32 v[166:167], v[36:37], v[38:39]
	v_pk_add_f32 v[160:161], v[160:161], v[162:163]
	v_pk_add_f32 v[164:165], v[164:165], v[166:167]
	v_pk_add_f32 v[160:161], v[160:161], v[164:165]
	v_add_f32_e32 v132, v160, v161
	v_pk_add_f32 v[168:169], v[80:81], v[82:83]
	v_pk_add_f32 v[170:171], v[84:85], v[86:87]
	v_pk_add_f32 v[172:173], v[88:89], v[90:91]
	v_pk_add_f32 v[174:175], v[92:93], v[94:95]
	v_pk_add_f32 v[168:169], v[168:169], v[170:171]
	v_pk_add_f32 v[172:173], v[172:173], v[174:175]
	v_pk_add_f32 v[168:169], v[168:169], v[172:173]
	v_add_f32_e32 v134, v168, v169
	v_pk_add_f32 v[160:161], v[48:49], v[50:51]
	v_pk_add_f32 v[162:163], v[52:53], v[54:55]
	v_pk_add_f32 v[164:165], v[64:65], v[66:67]
	v_pk_add_f32 v[166:167], v[76:77], v[78:79]
	v_pk_add_f32 v[160:161], v[160:161], v[162:163]
	v_pk_add_f32 v[164:165], v[164:165], v[166:167]
	v_pk_add_f32 v[160:161], v[160:161], v[164:165]
	v_add_f32_e32 v136, v160, v161
	v_pk_add_f32 v[168:169], v[100:101], v[102:103]
	v_pk_add_f32 v[170:171], v[112:113], v[114:115]
	v_pk_add_f32 v[172:173], v[120:121], v[122:123]
	v_pk_add_f32 v[174:175], v[124:125], v[126:127]
	v_pk_add_f32 v[168:169], v[168:169], v[170:171]
	v_pk_add_f32 v[172:173], v[172:173], v[174:175]
	v_pk_add_f32 v[168:169], v[168:169], v[172:173]
	v_add_f32_e32 v138, v168, v169
	v_pk_add_f32 v[160:161], v[96:97], v[98:99]
	v_pk_add_f32 v[162:163], v[104:105], v[106:107]
	v_pk_add_f32 v[164:165], v[108:109], v[110:111]
	v_pk_add_f32 v[166:167], v[116:117], v[118:119]
	v_pk_add_f32 v[160:161], v[160:161], v[162:163]
	v_pk_add_f32 v[164:165], v[164:165], v[166:167]
	v_pk_add_f32 v[160:161], v[160:161], v[164:165]
	v_add_f32_e32 v140, v160, v161
	v_mov_b32_e32 v129, v128
	v_mov_b32_e32 v131, v130
	v_mov_b32_e32 v133, v132
	v_mov_b32_e32 v135, v134
	v_mov_b32_e32 v137, v136
	v_mov_b32_e32 v139, v138
	v_mov_b32_e32 v141, v140
	v_permlane16_swap_b32_e32 v128, v129
	v_permlane16_swap_b32_e32 v130, v131
	v_permlane16_swap_b32_e32 v132, v133
	v_permlane16_swap_b32_e32 v134, v135
	v_permlane16_swap_b32_e32 v136, v137
	v_permlane16_swap_b32_e32 v138, v139
	v_permlane16_swap_b32_e32 v140, v141
	v_add_f32_e32 v128, v128, v129
	v_add_f32_e32 v130, v130, v131
	v_add_f32_e32 v132, v132, v133
	v_add_f32_e32 v134, v134, v135
	v_add_f32_e32 v136, v136, v137
	v_add_f32_e32 v138, v138, v139
	v_add_f32_e32 v140, v140, v141
	v_mov_b32_e32 v129, v128
	v_mov_b32_e32 v131, v130
	v_mov_b32_e32 v133, v132
	v_mov_b32_e32 v135, v134
	v_mov_b32_e32 v137, v136
	v_mov_b32_e32 v139, v138
	v_mov_b32_e32 v141, v140
	v_permlane32_swap_b32_e32 v128, v129
	v_permlane32_swap_b32_e32 v130, v131
	v_permlane32_swap_b32_e32 v132, v133
	v_permlane32_swap_b32_e32 v134, v135
	v_permlane32_swap_b32_e32 v136, v137
	v_permlane32_swap_b32_e32 v138, v139
	v_permlane32_swap_b32_e32 v140, v141
	v_add_f32_e32 v128, v128, v129
	v_add_f32_e32 v130, v130, v131
	v_add_f32_e32 v132, v132, v133
	v_add_f32_e32 v134, v134, v135
	v_add_f32_e32 v136, v136, v137
	v_add_f32_e32 v138, v138, v139
	v_add_f32_e32 v140, v140, v141
	v_pk_fma_f32 v[160:161], v[128:129], v[242:243], v[0:1] op_sel_hi:[0,0,1]
	v_pk_fma_f32 v[162:163], v[128:129], v[242:243], v[2:3] op_sel_hi:[0,0,1]
	v_pk_fma_f32 v[164:165], v[128:129], v[242:243], v[4:5] op_sel_hi:[0,0,1]
	v_pk_fma_f32 v[166:167], v[128:129], v[242:243], v[6:7] op_sel_hi:[0,0,1]
	v_pk_fma_f32 v[168:169], v[128:129], v[242:243], v[8:9] op_sel_hi:[0,0,1]
	v_pk_fma_f32 v[170:171], v[128:129], v[242:243], v[10:11] op_sel_hi:[0,0,1]
	v_pk_fma_f32 v[172:173], v[128:129], v[242:243], v[12:13] op_sel_hi:[0,0,1]
	v_pk_fma_f32 v[174:175], v[128:129], v[242:243], v[14:15] op_sel_hi:[0,0,1]
	v_pk_mul_f32 v[160:161], v[160:161], v[160:161]
	v_pk_mul_f32 v[162:163], v[162:163], v[162:163]
	v_pk_mul_f32 v[164:165], v[164:165], v[164:165]
	v_pk_mul_f32 v[166:167], v[166:167], v[166:167]
	v_pk_fma_f32 v[160:161], v[168:169], v[168:169], v[160:161]
	v_pk_fma_f32 v[162:163], v[170:171], v[170:171], v[162:163]
	v_pk_fma_f32 v[164:165], v[172:173], v[172:173], v[164:165]
	v_pk_fma_f32 v[166:167], v[174:175], v[174:175], v[166:167]
	v_pk_add_f32 v[160:161], v[160:161], v[162:163]
	v_pk_add_f32 v[164:165], v[164:165], v[166:167]
	v_pk_add_f32 v[160:161], v[160:161], v[164:165]
	v_add_f32_e32 v145, v160, v161
	v_pk_fma_f32 v[160:161], v[130:131], v[242:243], v[40:41] op_sel_hi:[0,0,1]
	v_pk_fma_f32 v[162:163], v[130:131], v[242:243], v[42:43] op_sel_hi:[0,0,1]
	v_pk_fma_f32 v[164:165], v[130:131], v[242:243], v[44:45] op_sel_hi:[0,0,1]
	v_pk_fma_f32 v[166:167], v[130:131], v[242:243], v[46:47] op_sel_hi:[0,0,1]
	v_pk_fma_f32 v[168:169], v[130:131], v[242:243], v[56:57] op_sel_hi:[0,0,1]
	v_pk_fma_f32 v[170:171], v[130:131], v[242:243], v[58:59] op_sel_hi:[0,0,1]
	v_pk_fma_f32 v[172:173], v[130:131], v[242:243], v[60:61] op_sel_hi:[0,0,1]
	v_pk_fma_f32 v[174:175], v[130:131], v[242:243], v[62:63] op_sel_hi:[0,0,1]
	v_pk_mul_f32 v[160:161], v[160:161], v[160:161]
	v_pk_mul_f32 v[162:163], v[162:163], v[162:163]
	v_pk_mul_f32 v[164:165], v[164:165], v[164:165]
	v_pk_mul_f32 v[166:167], v[166:167], v[166:167]
	v_pk_fma_f32 v[160:161], v[168:169], v[168:169], v[160:161]
	v_pk_fma_f32 v[162:163], v[170:171], v[170:171], v[162:163]
	v_pk_fma_f32 v[164:165], v[172:173], v[172:173], v[164:165]
	v_pk_fma_f32 v[166:167], v[174:175], v[174:175], v[166:167]
	v_pk_add_f32 v[160:161], v[160:161], v[162:163]
	v_pk_add_f32 v[164:165], v[164:165], v[166:167]
	v_pk_add_f32 v[160:161], v[160:161], v[164:165]
	v_add_f32_e32 v147, v160, v161
	v_pk_fma_f32 v[160:161], v[132:133], v[242:243], v[24:25] op_sel_hi:[0,0,1]
	v_pk_fma_f32 v[162:163], v[132:133], v[242:243], v[26:27] op_sel_hi:[0,0,1]
	v_pk_fma_f32 v[164:165], v[132:133], v[242:243], v[28:29] op_sel_hi:[0,0,1]
	v_pk_fma_f32 v[166:167], v[132:133], v[242:243], v[30:31] op_sel_hi:[0,0,1]
	v_pk_fma_f32 v[168:169], v[132:133], v[242:243], v[32:33] op_sel_hi:[0,0,1]
	v_pk_fma_f32 v[170:171], v[132:133], v[242:243], v[34:35] op_sel_hi:[0,0,1]
	v_pk_fma_f32 v[172:173], v[132:133], v[242:243], v[36:37] op_sel_hi:[0,0,1]
	v_pk_fma_f32 v[174:175], v[132:133], v[242:243], v[38:39] op_sel_hi:[0,0,1]
	v_pk_mul_f32 v[160:161], v[160:161], v[160:161]
	v_pk_mul_f32 v[162:163], v[162:163], v[162:163]
	v_pk_mul_f32 v[164:165], v[164:165], v[164:165]
	v_pk_mul_f32 v[166:167], v[166:167], v[166:167]
	v_pk_fma_f32 v[160:161], v[168:169], v[168:169], v[160:161]
	v_pk_fma_f32 v[162:163], v[170:171], v[170:171], v[162:163]
	v_pk_fma_f32 v[164:165], v[172:173], v[172:173], v[164:165]
	v_pk_fma_f32 v[166:167], v[174:175], v[174:175], v[166:167]
	v_pk_add_f32 v[160:161], v[160:161], v[162:163]
	v_pk_add_f32 v[164:165], v[164:165], v[166:167]
	v_pk_add_f32 v[160:161], v[160:161], v[164:165]
	v_add_f32_e32 v149, v160, v161
	v_pk_fma_f32 v[160:161], v[134:135], v[242:243], v[80:81] op_sel_hi:[0,0,1]
	v_pk_fma_f32 v[162:163], v[134:135], v[242:243], v[82:83] op_sel_hi:[0,0,1]
	v_pk_fma_f32 v[164:165], v[134:135], v[242:243], v[84:85] op_sel_hi:[0,0,1]
	v_pk_fma_f32 v[166:167], v[134:135], v[242:243], v[86:87] op_sel_hi:[0,0,1]
	v_pk_fma_f32 v[168:169], v[134:135], v[242:243], v[88:89] op_sel_hi:[0,0,1]
	v_pk_fma_f32 v[170:171], v[134:135], v[242:243], v[90:91] op_sel_hi:[0,0,1]
	v_pk_fma_f32 v[172:173], v[134:135], v[242:243], v[92:93] op_sel_hi:[0,0,1]
	v_pk_fma_f32 v[174:175], v[134:135], v[242:243], v[94:95] op_sel_hi:[0,0,1]
	v_pk_mul_f32 v[160:161], v[160:161], v[160:161]
	v_pk_mul_f32 v[162:163], v[162:163], v[162:163]
	v_pk_mul_f32 v[164:165], v[164:165], v[164:165]
	v_pk_mul_f32 v[166:167], v[166:167], v[166:167]
	v_pk_fma_f32 v[160:161], v[168:169], v[168:169], v[160:161]
	v_pk_fma_f32 v[162:163], v[170:171], v[170:171], v[162:163]
	v_pk_fma_f32 v[164:165], v[172:173], v[172:173], v[164:165]
	v_pk_fma_f32 v[166:167], v[174:175], v[174:175], v[166:167]
	v_pk_add_f32 v[160:161], v[160:161], v[162:163]
	v_pk_add_f32 v[164:165], v[164:165], v[166:167]
	v_pk_add_f32 v[160:161], v[160:161], v[164:165]
	v_add_f32_e32 v151, v160, v161
	v_pk_fma_f32 v[160:161], v[136:137], v[242:243], v[48:49] op_sel_hi:[0,0,1]
	v_pk_fma_f32 v[162:163], v[136:137], v[242:243], v[50:51] op_sel_hi:[0,0,1]
	v_pk_fma_f32 v[164:165], v[136:137], v[242:243], v[52:53] op_sel_hi:[0,0,1]
	v_pk_fma_f32 v[166:167], v[136:137], v[242:243], v[54:55] op_sel_hi:[0,0,1]
	v_pk_fma_f32 v[168:169], v[136:137], v[242:243], v[64:65] op_sel_hi:[0,0,1]
	v_pk_fma_f32 v[170:171], v[136:137], v[242:243], v[66:67] op_sel_hi:[0,0,1]
	v_pk_fma_f32 v[172:173], v[136:137], v[242:243], v[76:77] op_sel_hi:[0,0,1]
	v_pk_fma_f32 v[174:175], v[136:137], v[242:243], v[78:79] op_sel_hi:[0,0,1]
	v_pk_mul_f32 v[160:161], v[160:161], v[160:161]
	v_pk_mul_f32 v[162:163], v[162:163], v[162:163]
	v_pk_mul_f32 v[164:165], v[164:165], v[164:165]
	v_pk_mul_f32 v[166:167], v[166:167], v[166:167]
	v_pk_fma_f32 v[160:161], v[168:169], v[168:169], v[160:161]
	v_pk_fma_f32 v[162:163], v[170:171], v[170:171], v[162:163]
	v_pk_fma_f32 v[164:165], v[172:173], v[172:173], v[164:165]
	v_pk_fma_f32 v[166:167], v[174:175], v[174:175], v[166:167]
	v_pk_add_f32 v[160:161], v[160:161], v[162:163]
	v_pk_add_f32 v[164:165], v[164:165], v[166:167]
	v_pk_add_f32 v[160:161], v[160:161], v[164:165]
	v_add_f32_e32 v153, v160, v161
	v_pk_fma_f32 v[160:161], v[138:139], v[242:243], v[100:101] op_sel_hi:[0,0,1]
	v_pk_fma_f32 v[162:163], v[138:139], v[242:243], v[102:103] op_sel_hi:[0,0,1]
	v_pk_fma_f32 v[164:165], v[138:139], v[242:243], v[112:113] op_sel_hi:[0,0,1]
	v_pk_fma_f32 v[166:167], v[138:139], v[242:243], v[114:115] op_sel_hi:[0,0,1]
	v_pk_fma_f32 v[168:169], v[138:139], v[242:243], v[120:121] op_sel_hi:[0,0,1]
	v_pk_fma_f32 v[170:171], v[138:139], v[242:243], v[122:123] op_sel_hi:[0,0,1]
	v_pk_fma_f32 v[172:173], v[138:139], v[242:243], v[124:125] op_sel_hi:[0,0,1]
	v_pk_fma_f32 v[174:175], v[138:139], v[242:243], v[126:127] op_sel_hi:[0,0,1]
	v_pk_mul_f32 v[160:161], v[160:161], v[160:161]
	v_pk_mul_f32 v[162:163], v[162:163], v[162:163]
	v_pk_mul_f32 v[164:165], v[164:165], v[164:165]
	v_pk_mul_f32 v[166:167], v[166:167], v[166:167]
	v_pk_fma_f32 v[160:161], v[168:169], v[168:169], v[160:161]
	v_pk_fma_f32 v[162:163], v[170:171], v[170:171], v[162:163]
	v_pk_fma_f32 v[164:165], v[172:173], v[172:173], v[164:165]
	v_pk_fma_f32 v[166:167], v[174:175], v[174:175], v[166:167]
	v_pk_add_f32 v[160:161], v[160:161], v[162:163]
	v_pk_add_f32 v[164:165], v[164:165], v[166:167]
	v_pk_add_f32 v[160:161], v[160:161], v[164:165]
	v_add_f32_e32 v155, v160, v161
	v_pk_fma_f32 v[160:161], v[140:141], v[242:243], v[96:97] op_sel_hi:[0,0,1]
	v_pk_fma_f32 v[162:163], v[140:141], v[242:243], v[98:99] op_sel_hi:[0,0,1]
	v_pk_fma_f32 v[164:165], v[140:141], v[242:243], v[104:105] op_sel_hi:[0,0,1]
	v_pk_fma_f32 v[166:167], v[140:141], v[242:243], v[106:107] op_sel_hi:[0,0,1]
	v_pk_fma_f32 v[168:169], v[140:141], v[242:243], v[108:109] op_sel_hi:[0,0,1]
	v_pk_fma_f32 v[170:171], v[140:141], v[242:243], v[110:111] op_sel_hi:[0,0,1]
	v_pk_fma_f32 v[172:173], v[140:141], v[242:243], v[116:117] op_sel_hi:[0,0,1]
	v_pk_fma_f32 v[174:175], v[140:141], v[242:243], v[118:119] op_sel_hi:[0,0,1]
	v_pk_mul_f32 v[160:161], v[160:161], v[160:161]
	v_pk_mul_f32 v[162:163], v[162:163], v[162:163]
	v_pk_mul_f32 v[164:165], v[164:165], v[164:165]
	v_pk_mul_f32 v[166:167], v[166:167], v[166:167]
	v_pk_fma_f32 v[160:161], v[168:169], v[168:169], v[160:161]
	v_pk_fma_f32 v[162:163], v[170:171], v[170:171], v[162:163]
	v_pk_fma_f32 v[164:165], v[172:173], v[172:173], v[164:165]
	v_pk_fma_f32 v[166:167], v[174:175], v[174:175], v[166:167]
	v_pk_add_f32 v[160:161], v[160:161], v[162:163]
	v_pk_add_f32 v[164:165], v[164:165], v[166:167]
	v_pk_add_f32 v[160:161], v[160:161], v[164:165]
	v_add_f32_e32 v157, v160, v161
	v_mov_b32_e32 v144, v145
	v_mov_b32_e32 v146, v147
	v_mov_b32_e32 v148, v149
	v_mov_b32_e32 v150, v151
	v_mov_b32_e32 v152, v153
	v_mov_b32_e32 v154, v155
	v_mov_b32_e32 v156, v157
	v_permlane16_swap_b32_e32 v145, v144
	v_permlane16_swap_b32_e32 v147, v146
	v_permlane16_swap_b32_e32 v149, v148
	v_permlane16_swap_b32_e32 v151, v150
	v_permlane16_swap_b32_e32 v153, v152
	v_permlane16_swap_b32_e32 v155, v154
	v_permlane16_swap_b32_e32 v157, v156
	v_add_f32_e32 v145, v145, v144
	v_add_f32_e32 v147, v147, v146
	v_add_f32_e32 v149, v149, v148
	v_add_f32_e32 v151, v151, v150
	v_add_f32_e32 v153, v153, v152
	v_add_f32_e32 v155, v155, v154
	v_add_f32_e32 v157, v157, v156
	v_mov_b32_e32 v144, v145
	v_mov_b32_e32 v146, v147
	v_mov_b32_e32 v148, v149
	v_mov_b32_e32 v150, v151
	v_mov_b32_e32 v152, v153
	v_mov_b32_e32 v154, v155
	v_mov_b32_e32 v156, v157
	v_permlane32_swap_b32_e32 v145, v144
	v_permlane32_swap_b32_e32 v147, v146
	v_permlane32_swap_b32_e32 v149, v148
	v_permlane32_swap_b32_e32 v151, v150
	v_permlane32_swap_b32_e32 v153, v152
	v_permlane32_swap_b32_e32 v155, v154
	v_permlane32_swap_b32_e32 v157, v156
	v_add_f32_e32 v145, v145, v144
	v_add_f32_e32 v147, v147, v146
	v_add_f32_e32 v149, v149, v148
	v_add_f32_e32 v151, v151, v150
	v_add_f32_e32 v153, v153, v152
	v_add_f32_e32 v155, v155, v154
	v_add_f32_e32 v157, v157, v156
	s_and_saveexec_b64 s[12:13], s[4:5]
	v_mul_f32_e32 v144, 0x3c800000, v128
	v_mul_f32_e32 v146, 0x3c800000, v130
	v_mul_f32_e32 v148, 0x3c800000, v132
	v_mul_f32_e32 v150, 0x3c800000, v134
	v_mul_f32_e32 v152, 0x3c800000, v136
	v_mul_f32_e32 v154, 0x3c800000, v138
	v_mul_f32_e32 v156, 0x3c800000, v140
	ds_write_b64 v233, v[144:145] offset:512
	ds_write_b64 v233, v[146:147] offset:1024
	ds_write_b64 v233, v[148:149] offset:1536
	ds_write_b64 v233, v[150:151] offset:4096
	ds_write_b64 v233, v[152:153] offset:4608
	ds_write_b64 v233, v[154:155] offset:5120
	ds_write_b64 v233, v[156:157] offset:5632
